# attention key-tile loops: back edge reduced to one conditional branch (counter move hoisted above it) and the duplicate vmcnt(0) before the barrier removed
# baseline (speedup 1.0000x reference)
; DI float wave_max(float v) { for (int o = 32; o; o >>= 1) v = fmaxf(v, __shfl_xor(v, o)); return v; }
; template <int NKS>
; DI void attn_tile(const Params& p, int layer, int seq, int slot, int qt, char* smem, bool wr = true) {
;     ...
;   auto stage = [&](int kt) {
;     const int k0 = seq_start + kt * 128;
;     char* base = smem + (kt & 1) * 32768 + w * 1024;
; #pragma unroll
;     for (int i = 0; i < 4; ++i) {
;       __builtin_amdgcn_raw_ptr_buffer_load_lds(rK, (lds_ptr_t)(base + i * 4096), 16, voK, (k0 + 32 * i) * kstride * 2, 0, 0);
;       __builtin_amdgcn_raw_ptr_buffer_load_lds(rV, (lds_ptr_t)(base + 16384 + i * 4096), 16, voV,
;                                                (32 * (i & 1)) * (T_TOK * 2) + (k0 + 64 * (i >> 1)) * 2, 0, 0);
;     }
;   };
;   const int nkt = L >> 7;
;   const bool fast = wave_max(fmaxf(-ncb[0], -ncb[1])) < 60.f;
;   f32x4m ls4[2];
; #pragma unroll
;   for (int qb = 0; qb < 2; ++qb)
; #pragma unroll
;     for (int i = 0; i < 4; ++i) ls4[qb][i] = 0.f;
;   bf16x8 selA;
;   {
;     const int r16 = lane & 15, grp = lane >> 4;
;     const short one = ((r16 == 0 && (grp & 1) == 0) || (r16 == 1 && (grp & 1) == 1)) ? (short)0x3F80 : (short)0;
; #pragma unroll
;     for (int i = 0; i < 8; ++i) selA[i] = one;
;   }
;   auto mainloop = [&](auto SUBT) {
;     constexpr bool SUB = decltype(SUBT)::value;
;     for (int kt = 0; kt < nkt; ++kt) {
;       asm volatile("s_waitcnt vmcnt(0)" ::: "memory");
;       __syncthreads();
;       if (kt + 1 < nkt) stage(kt + 1);
; #pragma unroll 1
;       for (int kh = 0; kh < 2; ++kh) {
;       const u16* sK = (const u16*)(smem + (kt & 1) * 32768 + kh * 8192);
;       const u16* sV = (const u16*)(smem + (kt & 1) * 32768 + 16384 + kh * 8192);
;       auto kb_body = [&](int kb) {
;         bf16x8 kf[NKS];
; #pragma unroll
;         for (int ks = 0; ks < NKS; ++ks) kf[ks] = *(const bf16x8*)(sK + swz(32 * kb + r, 2 * (ks0 + ks) + h));
.LBB0_637:
	s_waitcnt vmcnt(0)
	s_lshl_b32 s4, s29, 15
	s_and_b32 s4, s4, 0x8000
	v_lshl_add_u32 v128, v187, 1, s4
	v_lshl_add_u32 v130, v188, 1, s4
	v_lshl_add_u32 v131, v189, 1, s4
	v_lshl_add_u32 v191, v190, 1, s4
	s_add_i32 s28, s29, 1
	s_cmp_ge_u32 s28, s25
	s_barrier
	ds_read_b128 v[192:195], v128
	ds_read_b128 v[196:199], v130
	ds_read_b128 v[200:203], v131
	ds_read_b128 v[204:207], v191
	ds_read_b128 v[208:211], v128 offset:4096
	ds_read_b128 v[212:215], v130 offset:4096
	ds_read_b128 v[216:219], v131 offset:4096
	ds_read_b128 v[220:223], v191 offset:4096
	ds_read_b128 v[224:227], v128 offset:16384
	ds_read_b128 v[228:231], v128 offset:20480
	s_cbranch_scc1 .LBB0_639
	s_lshl_b32 s4, s28, 15
	s_and_b32 s4, s4, 0x8000
	s_lshl_b32 s14, s28, 8
	s_add_i32 s4, s26, s4
	s_add_i32 s30, s14, s27
	s_add_i32 s5, s4, 0x4000
	s_lshl_b32 s31, s30, 7
	s_mov_b32 m0, s4
	s_mov_b32 s14, s10
	buffer_load_dwordx4 v185, s[8:11], s31 offen lds
	s_mov_b32 s15, s11
	s_mov_b32 m0, s5
	s_or_b32 s5, s31, 0x2000
	buffer_load_dwordx4 v186, s[12:15], s30 offen lds
	s_add_i32 m0, s4, 0x1000
	s_nop 0
	buffer_load_dwordx4 v185, s[8:11], s5 offen lds
	s_add_i32 m0, s4, 0x5000
	s_add_i32 s5, s30, 0x300000
	buffer_load_dwordx4 v186, s[12:15], s5 offen lds
	s_or_b32 s5, s30, 0x80
	s_add_i32 m0, s4, 0x2000
	s_lshl_b32 s34, s5, 7
	buffer_load_dwordx4 v185, s[8:11], s34 offen lds
	s_add_i32 m0, s4, 0x6000
	s_add_i32 s30, s30, 0x300080
	buffer_load_dwordx4 v186, s[12:15], s5 offen lds
	s_add_i32 m0, s4, 0x3000
	s_or_b32 s5, s31, 0x6000
	buffer_load_dwordx4 v185, s[8:11], s5 offen lds
	s_add_i32 m0, s4, 0x7000
	s_nop 0
	buffer_load_dwordx4 v186, s[12:15], s30 offen lds
.LBB0_639:
.LBB0_640:
	s_waitcnt lgkmcnt(8)
	v_mfma_f32_32x32x16_bf16 v[112:127], v[192:195], v[132:135], 0
	v_mfma_f32_32x32x16_bf16 v[112:127], v[196:199], v[136:139], v[112:127]
	s_waitcnt lgkmcnt(6)
	v_mfma_f32_32x32x16_bf16 v[112:127], v[200:203], v[140:143], v[112:127]
	v_mfma_f32_32x32x16_bf16 v[112:127], v[204:207], v[144:147], v[112:127]
	v_mfma_f32_32x32x16_bf16 v[96:111], v[192:195], v[148:151], 0
	v_mfma_f32_32x32x16_bf16 v[96:111], v[196:199], v[152:155], v[96:111]
	v_mfma_f32_32x32x16_bf16 v[96:111], v[200:203], v[156:159], v[96:111]
	v_mfma_f32_32x32x16_bf16 v[96:111], v[204:207], v[160:163], v[96:111]
	ds_read_b128 v[192:195], v130 offset:16384
	ds_read_b128 v[196:199], v130 offset:20480
	ds_read_b128 v[200:203], v131 offset:16384
	ds_read_b128 v[204:207], v131 offset:20480
	s_waitcnt lgkmcnt(9)
	v_mfma_f32_32x32x16_bf16 v[64:79], v[208:211], v[132:135], 0
	s_nop 1
	v_exp_f32_e32 v112, v112
	v_exp_f32_e32 v113, v113
	v_exp_f32_e32 v114, v114
	v_exp_f32_e32 v115, v115
	v_cvt_pk_bf16_f32 v112, v112, v113
	v_cvt_pk_bf16_f32 v113, v114, v115
	s_waitcnt lgkmcnt(6)
	v_mfma_f32_32x32x16_bf16 v[64:79], v[212:215], v[136:139], v[64:79]
	v_exp_f32_e32 v116, v116
	v_exp_f32_e32 v117, v117
	v_exp_f32_e32 v118, v118
	v_exp_f32_e32 v119, v119
	v_cvt_pk_bf16_f32 v114, v116, v117
	v_cvt_pk_bf16_f32 v115, v118, v119
	v_mfma_f32_32x32x16_bf16 v[64:79], v[216:219], v[140:143], v[64:79]
	v_exp_f32_e32 v120, v120
	v_exp_f32_e32 v121, v121
	v_exp_f32_e32 v122, v122
	v_exp_f32_e32 v123, v123
	v_cvt_pk_bf16_f32 v116, v120, v121
	v_cvt_pk_bf16_f32 v117, v122, v123
	v_mfma_f32_32x32x16_bf16 v[64:79], v[220:223], v[144:147], v[64:79]
	s_waitcnt lgkmcnt(4)
	v_mfma_f32_32x32x16_bf16 v[48:63], v[224:227], v[112:115], v[48:63]
	v_exp_f32_e32 v124, v124
	v_exp_f32_e32 v125, v125
	v_exp_f32_e32 v126, v126
	v_exp_f32_e32 v127, v127
	v_cvt_pk_bf16_f32 v118, v124, v125
	v_cvt_pk_bf16_f32 v119, v126, v127
	v_mfma_f32_32x32x16_bf16 v[80:95], v[208:211], v[148:151], 0
	v_mfma_f32_32x32x16_bf16 v[32:47], v[228:231], v[112:115], v[32:47]
	v_exp_f32_e32 v96, v96
	v_exp_f32_e32 v97, v97
	v_exp_f32_e32 v98, v98
	v_exp_f32_e32 v99, v99
	v_cvt_pk_bf16_f32 v96, v96, v97
	v_cvt_pk_bf16_f32 v97, v98, v99
	v_mfma_f32_16x16x32_bf16 v[164:167], v[172:175], v[112:115], v[164:167]
	v_mfma_f32_32x32x16_bf16 v[80:95], v[212:215], v[152:155], v[80:95]
	v_exp_f32_e32 v100, v100
	v_exp_f32_e32 v101, v101
	v_exp_f32_e32 v102, v102
	v_exp_f32_e32 v103, v103
	v_cvt_pk_bf16_f32 v98, v100, v101
	v_cvt_pk_bf16_f32 v99, v102, v103
	v_mfma_f32_32x32x16_bf16 v[80:95], v[216:219], v[156:159], v[80:95]
	s_waitcnt lgkmcnt(2)
	v_mfma_f32_32x32x16_bf16 v[48:63], v[192:195], v[116:119], v[48:63]
	v_exp_f32_e32 v104, v104
	v_exp_f32_e32 v105, v105
	v_exp_f32_e32 v106, v106
	v_exp_f32_e32 v107, v107
	v_cvt_pk_bf16_f32 v100, v104, v105
	v_cvt_pk_bf16_f32 v101, v106, v107
	v_mfma_f32_32x32x16_bf16 v[32:47], v[196:199], v[116:119], v[32:47]
	v_mfma_f32_16x16x32_bf16 v[164:167], v[172:175], v[116:119], v[164:167]
	v_exp_f32_e32 v108, v108
	v_exp_f32_e32 v109, v109
	v_exp_f32_e32 v110, v110
	v_exp_f32_e32 v111, v111
	v_cvt_pk_bf16_f32 v102, v108, v109
	v_cvt_pk_bf16_f32 v103, v110, v111
	v_mfma_f32_32x32x16_bf16 v[80:95], v[220:223], v[160:163], v[80:95]
	ds_read_b128 v[208:211], v191 offset:16384
	ds_read_b128 v[212:215], v191 offset:20480
	v_mfma_f32_32x32x16_bf16 v[16:31], v[224:227], v[96:99], v[16:31]
	v_exp_f32_e32 v64, v64
	v_exp_f32_e32 v65, v65
	v_exp_f32_e32 v66, v66
	v_exp_f32_e32 v67, v67
	v_cvt_pk_bf16_f32 v64, v64, v65
	v_cvt_pk_bf16_f32 v65, v66, v67
	v_mfma_f32_32x32x16_bf16 v[0:15], v[228:231], v[96:99], v[0:15]
	v_mfma_f32_16x16x32_bf16 v[168:171], v[172:175], v[96:99], v[168:171]
	v_exp_f32_e32 v68, v68
	v_exp_f32_e32 v69, v69
	v_exp_f32_e32 v70, v70
	v_exp_f32_e32 v71, v71
	v_cvt_pk_bf16_f32 v66, v68, v69
	v_cvt_pk_bf16_f32 v67, v70, v71
	v_mfma_f32_32x32x16_bf16 v[16:31], v[192:195], v[100:103], v[16:31]
	v_mfma_f32_32x32x16_bf16 v[0:15], v[196:199], v[100:103], v[0:15]
	v_exp_f32_e32 v72, v72
	v_exp_f32_e32 v73, v73
	v_exp_f32_e32 v74, v74
	v_exp_f32_e32 v75, v75
	v_cvt_pk_bf16_f32 v68, v72, v73
	v_cvt_pk_bf16_f32 v69, v74, v75
	v_mfma_f32_16x16x32_bf16 v[168:171], v[172:175], v[100:103], v[168:171]
	s_waitcnt lgkmcnt(2)
; #define MFMA32(a, b, c) __builtin_amdgcn_mfma_f32_32x32x16_bf16((a), (b), (c), 0, 0, 0)
; DI float fadd1(float a, float b) { float r; asm("v_add_f32 %0, %1, %2" : "=v"(r) : "v"(a), "v"(b)); return r; }
; template <int NKS>
; DI void attn_tile(const Params& p, int layer, int seq, int slot, int qt, char* smem, bool wr = true) {
;     ...
;       auto kb_body = [&](int kb) {
;         bf16x8 kf[NKS];
; #pragma unroll
;         for (int ks = 0; ks < NKS; ++ks) kf[ks] = *(const bf16x8*)(sK + swz(32 * kb + r, 2 * (ks0 + ks) + h));
;         bf16x8 pk[2][2];
; #pragma unroll
;         for (int qb = 0; qb < 2; ++qb) {
;           f32x16 st;
; #pragma unroll
;           for (int i = 0; i < 16; ++i) st[i] = SUB ? ncb[qb] : 0.f;
; #pragma unroll
;           for (int ks = 0; ks < NKS; ++ks) st = MFMA32(kf[ks], qf[qb][ks], st);
;           if constexpr (SUB) {
;             float ls = 0.f;
; #pragma unroll
;             for (int i = 0; i < 16; ++i) { float e = __builtin_amdgcn_exp2f(st[i]); st[i] = e; ls = fadd1(ls, e); }
;             lsum[qb] += ls;
;             pk[qb][0] = pack8(st, 0); pk[qb][1] = pack8(st, 1);
;           } else {
; #pragma unroll
;             for (int i = 0; i < 16; ++i) st[i] = __builtin_amdgcn_exp2f(st[i]);
;             pk[qb][0] = pack8(st, 0); pk[qb][1] = pack8(st, 1);
;             ls4[qb] = __builtin_amdgcn_mfma_f32_16x16x32_bf16(selA, pk[qb][0], ls4[qb], 0, 0, 0);
;             ls4[qb] = __builtin_amdgcn_mfma_f32_16x16x32_bf16(selA, pk[qb][1], ls4[qb], 0, 0, 0);
;           }
;         }
; #pragma unroll
;         for (int eb = 0; eb < 2; ++eb)
; #pragma unroll
;           for (int s2 = 0; s2 < 2; ++s2) {
;             bf16x8 vf = *(const bf16x8*)(sV + swz(32 * eb + r, 4 * kb + 2 * s2 + h));
; #pragma unroll
;             for (int qb = 0; qb < 2; ++qb) O[qb][eb] = MFMA32(vf, pk[qb][s2], O[qb][eb]);
;           }
;       };
	v_mfma_f32_32x32x16_bf16 v[48:63], v[200:203], v[64:67], v[48:63]
	v_exp_f32_e32 v76, v76
	v_exp_f32_e32 v77, v77
	v_exp_f32_e32 v78, v78
	v_exp_f32_e32 v79, v79
	v_cvt_pk_bf16_f32 v70, v76, v77
	v_cvt_pk_bf16_f32 v71, v78, v79
	v_mfma_f32_32x32x16_bf16 v[32:47], v[204:207], v[64:67], v[32:47]
	v_mfma_f32_16x16x32_bf16 v[164:167], v[172:175], v[64:67], v[164:167]
	v_exp_f32_e32 v80, v80
	v_exp_f32_e32 v81, v81
	v_exp_f32_e32 v82, v82
	v_exp_f32_e32 v83, v83
	v_cvt_pk_bf16_f32 v80, v80, v81
	v_cvt_pk_bf16_f32 v81, v82, v83
	s_waitcnt lgkmcnt(0)
	v_mfma_f32_32x32x16_bf16 v[48:63], v[208:211], v[68:71], v[48:63]
	v_exp_f32_e32 v84, v84
	v_exp_f32_e32 v85, v85
	v_exp_f32_e32 v86, v86
	v_exp_f32_e32 v87, v87
	v_cvt_pk_bf16_f32 v82, v84, v85
	v_cvt_pk_bf16_f32 v83, v86, v87
	v_mfma_f32_32x32x16_bf16 v[32:47], v[212:215], v[68:71], v[32:47]
	v_mfma_f32_16x16x32_bf16 v[164:167], v[172:175], v[68:71], v[164:167]
	v_exp_f32_e32 v88, v88
	v_exp_f32_e32 v89, v89
	v_exp_f32_e32 v90, v90
	v_exp_f32_e32 v91, v91
	v_cvt_pk_bf16_f32 v84, v88, v89
	v_cvt_pk_bf16_f32 v85, v90, v91
	v_mfma_f32_32x32x16_bf16 v[16:31], v[200:203], v[80:83], v[16:31]
	v_exp_f32_e32 v92, v92
	v_exp_f32_e32 v93, v93
	v_exp_f32_e32 v94, v94
	v_exp_f32_e32 v95, v95
	v_cvt_pk_bf16_f32 v86, v92, v93
	v_cvt_pk_bf16_f32 v87, v94, v95
	v_mfma_f32_32x32x16_bf16 v[0:15], v[204:207], v[80:83], v[0:15]
	v_mfma_f32_16x16x32_bf16 v[168:171], v[172:175], v[80:83], v[168:171]
	v_mfma_f32_32x32x16_bf16 v[16:31], v[208:211], v[84:87], v[16:31]
	v_mfma_f32_32x32x16_bf16 v[0:15], v[212:215], v[84:87], v[0:15]
	v_mfma_f32_16x16x32_bf16 v[168:171], v[172:175], v[84:87], v[168:171]
	ds_read_b128 v[192:195], v128 offset:8192
	ds_read_b128 v[196:199], v130 offset:8192
	ds_read_b128 v[200:203], v131 offset:8192
	ds_read_b128 v[204:207], v191 offset:8192
	ds_read_b128 v[208:211], v128 offset:12288
	ds_read_b128 v[212:215], v130 offset:12288
	ds_read_b128 v[216:219], v131 offset:12288
	ds_read_b128 v[220:223], v191 offset:12288
	ds_read_b128 v[224:227], v128 offset:24576
	ds_read_b128 v[228:231], v128 offset:28672
	s_waitcnt lgkmcnt(8)
	v_mfma_f32_32x32x16_bf16 v[112:127], v[192:195], v[132:135], 0
	v_mfma_f32_32x32x16_bf16 v[112:127], v[196:199], v[136:139], v[112:127]
	s_waitcnt lgkmcnt(6)
	v_mfma_f32_32x32x16_bf16 v[112:127], v[200:203], v[140:143], v[112:127]
	v_mfma_f32_32x32x16_bf16 v[112:127], v[204:207], v[144:147], v[112:127]
	v_mfma_f32_32x32x16_bf16 v[96:111], v[192:195], v[148:151], 0
	v_mfma_f32_32x32x16_bf16 v[96:111], v[196:199], v[152:155], v[96:111]
	v_mfma_f32_32x32x16_bf16 v[96:111], v[200:203], v[156:159], v[96:111]
	v_mfma_f32_32x32x16_bf16 v[96:111], v[204:207], v[160:163], v[96:111]
	ds_read_b128 v[192:195], v130 offset:24576
	ds_read_b128 v[196:199], v130 offset:28672
	ds_read_b128 v[200:203], v131 offset:24576
	ds_read_b128 v[204:207], v131 offset:28672
	s_waitcnt lgkmcnt(9)
	v_mfma_f32_32x32x16_bf16 v[64:79], v[208:211], v[132:135], 0
	s_nop 1
	v_exp_f32_e32 v112, v112
	v_exp_f32_e32 v113, v113
	v_exp_f32_e32 v114, v114
	v_exp_f32_e32 v115, v115
	v_cvt_pk_bf16_f32 v112, v112, v113
	v_cvt_pk_bf16_f32 v113, v114, v115
	s_waitcnt lgkmcnt(6)
	v_mfma_f32_32x32x16_bf16 v[64:79], v[212:215], v[136:139], v[64:79]
	v_exp_f32_e32 v116, v116
	v_exp_f32_e32 v117, v117
	v_exp_f32_e32 v118, v118
	v_exp_f32_e32 v119, v119
	v_cvt_pk_bf16_f32 v114, v116, v117
	v_cvt_pk_bf16_f32 v115, v118, v119
	v_mfma_f32_32x32x16_bf16 v[64:79], v[216:219], v[140:143], v[64:79]
	v_exp_f32_e32 v120, v120
	v_exp_f32_e32 v121, v121
	v_exp_f32_e32 v122, v122
	v_exp_f32_e32 v123, v123
	v_cvt_pk_bf16_f32 v116, v120, v121
	v_cvt_pk_bf16_f32 v117, v122, v123
	v_mfma_f32_32x32x16_bf16 v[64:79], v[220:223], v[144:147], v[64:79]
	s_waitcnt lgkmcnt(4)
; #define MFMA32(a, b, c) __builtin_amdgcn_mfma_f32_32x32x16_bf16((a), (b), (c), 0, 0, 0)
; DI float fadd1(float a, float b) { float r; asm("v_add_f32 %0, %1, %2" : "=v"(r) : "v"(a), "v"(b)); return r; }
; template <int NKS>
; DI void attn_tile(const Params& p, int layer, int seq, int slot, int qt, char* smem, bool wr = true) {
;     ...
;       auto kb_body = [&](int kb) {
;         bf16x8 kf[NKS];
; #pragma unroll
;         for (int ks = 0; ks < NKS; ++ks) kf[ks] = *(const bf16x8*)(sK + swz(32 * kb + r, 2 * (ks0 + ks) + h));
;         bf16x8 pk[2][2];
; #pragma unroll
;         for (int qb = 0; qb < 2; ++qb) {
;           f32x16 st;
; #pragma unroll
;           for (int i = 0; i < 16; ++i) st[i] = SUB ? ncb[qb] : 0.f;
; #pragma unroll
;           for (int ks = 0; ks < NKS; ++ks) st = MFMA32(kf[ks], qf[qb][ks], st);
;           if constexpr (SUB) {
;             float ls = 0.f;
; #pragma unroll
;             for (int i = 0; i < 16; ++i) { float e = __builtin_amdgcn_exp2f(st[i]); st[i] = e; ls = fadd1(ls, e); }
;             lsum[qb] += ls;
;             pk[qb][0] = pack8(st, 0); pk[qb][1] = pack8(st, 1);
;           } else {
; #pragma unroll
;             for (int i = 0; i < 16; ++i) st[i] = __builtin_amdgcn_exp2f(st[i]);
;             pk[qb][0] = pack8(st, 0); pk[qb][1] = pack8(st, 1);
;             ls4[qb] = __builtin_amdgcn_mfma_f32_16x16x32_bf16(selA, pk[qb][0], ls4[qb], 0, 0, 0);
;             ls4[qb] = __builtin_amdgcn_mfma_f32_16x16x32_bf16(selA, pk[qb][1], ls4[qb], 0, 0, 0);
;           }
;         }
; #pragma unroll
;         for (int eb = 0; eb < 2; ++eb)
; #pragma unroll
;           for (int s2 = 0; s2 < 2; ++s2) {
;             bf16x8 vf = *(const bf16x8*)(sV + swz(32 * eb + r, 4 * kb + 2 * s2 + h));
; #pragma unroll
;             for (int qb = 0; qb < 2; ++qb) O[qb][eb] = MFMA32(vf, pk[qb][s2], O[qb][eb]);
	v_mfma_f32_32x32x16_bf16 v[48:63], v[224:227], v[112:115], v[48:63]
	v_exp_f32_e32 v124, v124
	v_exp_f32_e32 v125, v125
	v_exp_f32_e32 v126, v126
	v_exp_f32_e32 v127, v127
	v_cvt_pk_bf16_f32 v118, v124, v125
	v_cvt_pk_bf16_f32 v119, v126, v127
	v_mfma_f32_32x32x16_bf16 v[80:95], v[208:211], v[148:151], 0
	v_mfma_f32_32x32x16_bf16 v[32:47], v[228:231], v[112:115], v[32:47]
	v_exp_f32_e32 v96, v96
	v_exp_f32_e32 v97, v97
	v_exp_f32_e32 v98, v98
	v_exp_f32_e32 v99, v99
	v_cvt_pk_bf16_f32 v96, v96, v97
	v_cvt_pk_bf16_f32 v97, v98, v99
	v_mfma_f32_16x16x32_bf16 v[164:167], v[172:175], v[112:115], v[164:167]
	v_mfma_f32_32x32x16_bf16 v[80:95], v[212:215], v[152:155], v[80:95]
	v_exp_f32_e32 v100, v100
	v_exp_f32_e32 v101, v101
	v_exp_f32_e32 v102, v102
	v_exp_f32_e32 v103, v103
	v_cvt_pk_bf16_f32 v98, v100, v101
	v_cvt_pk_bf16_f32 v99, v102, v103
	v_mfma_f32_32x32x16_bf16 v[80:95], v[216:219], v[156:159], v[80:95]
	s_waitcnt lgkmcnt(2)
	v_mfma_f32_32x32x16_bf16 v[48:63], v[192:195], v[116:119], v[48:63]
	v_exp_f32_e32 v104, v104
	v_exp_f32_e32 v105, v105
	v_exp_f32_e32 v106, v106
	v_exp_f32_e32 v107, v107
	v_cvt_pk_bf16_f32 v100, v104, v105
	v_cvt_pk_bf16_f32 v101, v106, v107
	v_mfma_f32_32x32x16_bf16 v[32:47], v[196:199], v[116:119], v[32:47]
	v_mfma_f32_16x16x32_bf16 v[164:167], v[172:175], v[116:119], v[164:167]
	v_exp_f32_e32 v108, v108
	v_exp_f32_e32 v109, v109
	v_exp_f32_e32 v110, v110
	v_exp_f32_e32 v111, v111
	v_cvt_pk_bf16_f32 v102, v108, v109
	v_cvt_pk_bf16_f32 v103, v110, v111
	v_mfma_f32_32x32x16_bf16 v[80:95], v[220:223], v[160:163], v[80:95]
	ds_read_b128 v[208:211], v191 offset:24576
	ds_read_b128 v[212:215], v191 offset:28672
	v_mfma_f32_32x32x16_bf16 v[16:31], v[224:227], v[96:99], v[16:31]
	v_exp_f32_e32 v64, v64
	v_exp_f32_e32 v65, v65
	v_exp_f32_e32 v66, v66
	v_exp_f32_e32 v67, v67
	v_cvt_pk_bf16_f32 v64, v64, v65
	v_cvt_pk_bf16_f32 v65, v66, v67
	v_mfma_f32_32x32x16_bf16 v[0:15], v[228:231], v[96:99], v[0:15]
	v_mfma_f32_16x16x32_bf16 v[168:171], v[172:175], v[96:99], v[168:171]
	v_exp_f32_e32 v68, v68
	v_exp_f32_e32 v69, v69
	v_exp_f32_e32 v70, v70
	v_exp_f32_e32 v71, v71
	v_cvt_pk_bf16_f32 v66, v68, v69
	v_cvt_pk_bf16_f32 v67, v70, v71
	v_mfma_f32_32x32x16_bf16 v[16:31], v[192:195], v[100:103], v[16:31]
	v_mfma_f32_32x32x16_bf16 v[0:15], v[196:199], v[100:103], v[0:15]
	v_exp_f32_e32 v72, v72
	v_exp_f32_e32 v73, v73
	v_exp_f32_e32 v74, v74
	v_exp_f32_e32 v75, v75
	v_cvt_pk_bf16_f32 v68, v72, v73
	v_cvt_pk_bf16_f32 v69, v74, v75
	v_mfma_f32_16x16x32_bf16 v[168:171], v[172:175], v[100:103], v[168:171]
	s_waitcnt lgkmcnt(2)
	v_mfma_f32_32x32x16_bf16 v[48:63], v[200:203], v[64:67], v[48:63]
	v_exp_f32_e32 v76, v76
	v_exp_f32_e32 v77, v77
	v_exp_f32_e32 v78, v78
	v_exp_f32_e32 v79, v79
	v_cvt_pk_bf16_f32 v70, v76, v77
	v_cvt_pk_bf16_f32 v71, v78, v79
	v_mfma_f32_32x32x16_bf16 v[32:47], v[204:207], v[64:67], v[32:47]
	v_mfma_f32_16x16x32_bf16 v[164:167], v[172:175], v[64:67], v[164:167]
	v_exp_f32_e32 v80, v80
	v_exp_f32_e32 v81, v81
	v_exp_f32_e32 v82, v82
	v_exp_f32_e32 v83, v83
	v_cvt_pk_bf16_f32 v80, v80, v81
	v_cvt_pk_bf16_f32 v81, v82, v83
	s_waitcnt lgkmcnt(0)
	v_mfma_f32_32x32x16_bf16 v[48:63], v[208:211], v[68:71], v[48:63]
	v_exp_f32_e32 v84, v84
	v_exp_f32_e32 v85, v85
	v_exp_f32_e32 v86, v86
	v_exp_f32_e32 v87, v87
	v_cvt_pk_bf16_f32 v82, v84, v85
	v_cvt_pk_bf16_f32 v83, v86, v87
	v_mfma_f32_32x32x16_bf16 v[32:47], v[212:215], v[68:71], v[32:47]
	v_mfma_f32_16x16x32_bf16 v[164:167], v[172:175], v[68:71], v[164:167]
	v_exp_f32_e32 v88, v88
	v_exp_f32_e32 v89, v89
	v_exp_f32_e32 v90, v90
	v_exp_f32_e32 v91, v91
	v_cvt_pk_bf16_f32 v84, v88, v89
	v_cvt_pk_bf16_f32 v85, v90, v91
	v_mfma_f32_32x32x16_bf16 v[16:31], v[200:203], v[80:83], v[16:31]
	v_exp_f32_e32 v92, v92
	v_exp_f32_e32 v93, v93
	v_exp_f32_e32 v94, v94
	v_exp_f32_e32 v95, v95
	v_cvt_pk_bf16_f32 v86, v92, v93
	v_cvt_pk_bf16_f32 v87, v94, v95
	v_mfma_f32_32x32x16_bf16 v[0:15], v[204:207], v[80:83], v[0:15]
	v_mfma_f32_16x16x32_bf16 v[168:171], v[172:175], v[80:83], v[168:171]
	v_mfma_f32_32x32x16_bf16 v[16:31], v[208:211], v[84:87], v[16:31]
	v_mfma_f32_32x32x16_bf16 v[0:15], v[212:215], v[84:87], v[0:15]
	v_mfma_f32_16x16x32_bf16 v[168:171], v[172:175], v[84:87], v[168:171]
	s_cmp_eq_u32 s28, s25
	s_mov_b32 s29, s28
	s_cbranch_scc0 .LBB0_637

; template <int NKS>
; DI void attn_tile(const Params& p, int layer, int seq, int slot, int qt, char* smem, bool wr = true) {
;     ...
;   auto stage = [&](int kt) {
;     const int k0 = seq_start + kt * 128;
;     char* base = smem + (kt & 1) * 32768 + w * 1024;
; #pragma unroll
;     for (int i = 0; i < 4; ++i) {
;       __builtin_amdgcn_raw_ptr_buffer_load_lds(rK, (lds_ptr_t)(base + i * 4096), 16, voK, (k0 + 32 * i) * kstride * 2, 0, 0);
;     ...
;     for (int kt = 0; kt < nkt; ++kt) {
;       asm volatile("s_waitcnt vmcnt(0)" ::: "memory");
;       __syncthreads();
;       if (kt + 1 < nkt) stage(kt + 1);
; #pragma unroll 1
;       for (int kh = 0; kh < 2; ++kh) {
;       const u16* sK = (const u16*)(smem + (kt & 1) * 32768 + kh * 8192);
;       const u16* sV = (const u16*)(smem + (kt & 1) * 32768 + 16384 + kh * 8192);
;       auto kb_body = [&](int kb) {
;         bf16x8 kf[NKS];
; #pragma unroll
;         for (int ks = 0; ks < NKS; ++ks) kf[ks] = *(const bf16x8*)(sK + swz(32 * kb + r, 2 * (ks0 + ks) + h));
;         bf16x8 pk[2][2];
; #pragma unroll
;         for (int qb = 0; qb < 2; ++qb) {
;           f32x16 st;
; #pragma unroll
;           for (int i = 0; i < 16; ++i) st[i] = SUB ? ncb[qb] : 0.f;
; #pragma unroll
;           for (int ks = 0; ks < NKS; ++ks) st = MFMA32(kf[ks], qf[qb][ks], st);
;           if constexpr (SUB) {
;             float ls = 0.f;
; #pragma unroll
;             for (int i = 0; i < 16; ++i) { float e = __builtin_amdgcn_exp2f(st[i]); st[i] = e; ls = fadd1(ls, e); }
;             lsum[qb] += ls;
;             pk[qb][0] = pack8(st, 0); pk[qb][1] = pack8(st, 1);
;           } else {
; #pragma unroll
;             for (int i = 0; i < 16; ++i) st[i] = __builtin_amdgcn_exp2f(st[i]);
;             pk[qb][0] = pack8(st, 0); pk[qb][1] = pack8(st, 1);
;             ls4[qb] = __builtin_amdgcn_mfma_f32_16x16x32_bf16(selA, pk[qb][0], ls4[qb], 0, 0, 0);
;             ls4[qb] = __builtin_amdgcn_mfma_f32_16x16x32_bf16(selA, pk[qb][1], ls4[qb], 0, 0, 0);
;           }
;         }
; #pragma unroll
;         for (int eb = 0; eb < 2; ++eb)
; #pragma unroll
;           for (int s2 = 0; s2 < 2; ++s2) {
;             bf16x8 vf = *(const bf16x8*)(sV + swz(32 * eb + r, 4 * kb + 2 * s2 + h));
; #pragma unroll
;             for (int qb = 0; qb < 2; ++qb) O[qb][eb] = MFMA32(vf, pk[qb][s2], O[qb][eb]);
.LBB0_671:
	s_waitcnt vmcnt(0)
	s_lshl_b32 s4, s37, 15
	s_and_b32 s4, s4, 0x8000
	v_add3_u32 v128, s4, v172, v178
	v_add3_u32 v130, s4, v173, v178
	v_add3_u32 v131, s4, v174, v178
	v_add3_u32 v188, s4, v175, v178
	v_add3_u32 v189, s4, v176, v178
	v_add3_u32 v190, s4, v177, v178
	s_add_i32 s36, s37, 1
	s_cmp_ge_u32 s36, s31
	s_barrier
	ds_read_b128 v[180:183], v128
	ds_read_b128 v[184:187], v130
	ds_read_b128 v[204:207], v128 offset:4096
	ds_read_b128 v[208:211], v130 offset:4096
	ds_read_b128 v[212:215], v131 offset:16384
	ds_read_b128 v[216:219], v131 offset:20480
	ds_read_b128 v[220:223], v188 offset:16384
	ds_read_b128 v[224:227], v188 offset:20480
	ds_read_b128 v[228:231], v189 offset:16384
	s_cbranch_scc1 .LBB0_673
	s_lshl_b32 s4, s36, 15
	s_and_b32 s4, s4, 0x8000
	s_lshl_b32 s14, s36, 8
	s_add_i32 s4, s34, s4
	s_add_i32 s38, s14, s35
	s_add_i32 s5, s4, 0x4000
	s_lshl_b32 s39, s38, 8
	s_mov_b32 m0, s4
	s_mov_b32 s14, s10
	buffer_load_dwordx4 v170, s[8:11], s39 offen lds
	s_mov_b32 s15, s11
	s_mov_b32 m0, s5
	s_or_b32 s5, s39, 0x4000
	buffer_load_dwordx4 v171, s[12:15], s38 offen lds
	s_add_i32 m0, s4, 0x1000
	s_nop 0
	buffer_load_dwordx4 v170, s[8:11], s5 offen lds
	s_add_i32 m0, s4, 0x5000
	s_add_i32 s5, s38, 0x300000
	buffer_load_dwordx4 v171, s[12:15], s5 offen lds
	s_or_b32 s5, s38, 0x80
	s_add_i32 m0, s4, 0x2000
	s_lshl_b32 s40, s5, 8
	buffer_load_dwordx4 v170, s[8:11], s40 offen lds
	s_add_i32 m0, s4, 0x6000
	s_add_i32 s38, s38, 0x300080
	buffer_load_dwordx4 v171, s[12:15], s5 offen lds
	s_add_i32 m0, s4, 0x3000
	s_or_b32 s5, s39, 0xc000
	buffer_load_dwordx4 v170, s[8:11], s5 offen lds
	s_add_i32 m0, s4, 0x7000
	s_nop 0
	buffer_load_dwordx4 v171, s[12:15], s38 offen lds
.LBB0_673:
.LBB0_674:
	s_waitcnt lgkmcnt(7)
	v_mfma_f32_32x32x16_bf16 v[112:127], v[180:183], v[132:135], 0
	v_mfma_f32_32x32x16_bf16 v[112:127], v[184:187], v[136:139], v[112:127]
	v_mfma_f32_32x32x16_bf16 v[96:111], v[180:183], v[140:143], 0
	v_mfma_f32_32x32x16_bf16 v[96:111], v[184:187], v[144:147], v[96:111]
	ds_read_b128 v[180:183], v189 offset:20480
	ds_read_b128 v[184:187], v190 offset:16384
	s_waitcnt lgkmcnt(7)
	v_mfma_f32_32x32x16_bf16 v[64:79], v[204:207], v[132:135], 0
	v_mfma_f32_32x32x16_bf16 v[64:79], v[208:211], v[136:139], v[64:79]
	s_nop 4
	v_exp_f32_e32 v112, v112
	v_exp_f32_e32 v113, v113
	v_exp_f32_e32 v114, v114
	v_exp_f32_e32 v115, v115
	v_cvt_pk_bf16_f32 v112, v112, v113
	v_cvt_pk_bf16_f32 v113, v114, v115
	v_mfma_f32_32x32x16_bf16 v[80:95], v[204:207], v[140:143], 0
	ds_read_b128 v[204:207], v190 offset:20480
	v_exp_f32_e32 v116, v116
	v_exp_f32_e32 v117, v117
	v_exp_f32_e32 v118, v118
	v_exp_f32_e32 v119, v119
	v_cvt_pk_bf16_f32 v114, v116, v117
	v_cvt_pk_bf16_f32 v115, v118, v119
	v_mfma_f32_32x32x16_bf16 v[80:95], v[208:211], v[144:147], v[80:95]
	v_exp_f32_e32 v120, v120
	v_exp_f32_e32 v121, v121
	v_exp_f32_e32 v122, v122
	v_exp_f32_e32 v123, v123
	v_cvt_pk_bf16_f32 v116, v120, v121
	v_cvt_pk_bf16_f32 v117, v122, v123
	s_waitcnt lgkmcnt(6)
	v_mfma_f32_32x32x16_bf16 v[48:63], v[212:215], v[112:115], v[48:63]
	v_exp_f32_e32 v124, v124
	v_exp_f32_e32 v125, v125
	v_exp_f32_e32 v126, v126
	v_exp_f32_e32 v127, v127
	v_cvt_pk_bf16_f32 v118, v124, v125
	v_cvt_pk_bf16_f32 v119, v126, v127
	v_mfma_f32_32x32x16_bf16 v[32:47], v[216:219], v[112:115], v[32:47]
	v_exp_f32_e32 v96, v96
	v_exp_f32_e32 v97, v97
	v_exp_f32_e32 v98, v98
	v_exp_f32_e32 v99, v99
	v_cvt_pk_bf16_f32 v96, v96, v97
	v_cvt_pk_bf16_f32 v97, v98, v99
	v_mfma_f32_16x16x32_bf16 v[148:151], v[156:159], v[112:115], v[148:151]
	s_waitcnt lgkmcnt(4)
	v_mfma_f32_32x32x16_bf16 v[48:63], v[220:223], v[116:119], v[48:63]
	v_exp_f32_e32 v100, v100
	v_exp_f32_e32 v101, v101
	v_exp_f32_e32 v102, v102
	v_exp_f32_e32 v103, v103
	v_cvt_pk_bf16_f32 v98, v100, v101
	v_cvt_pk_bf16_f32 v99, v102, v103
	v_mfma_f32_32x32x16_bf16 v[32:47], v[224:227], v[116:119], v[32:47]
	v_mfma_f32_16x16x32_bf16 v[148:151], v[156:159], v[116:119], v[148:151]
	v_exp_f32_e32 v104, v104
	v_exp_f32_e32 v105, v105
	v_exp_f32_e32 v106, v106
	v_exp_f32_e32 v107, v107
	v_cvt_pk_bf16_f32 v100, v104, v105
	v_cvt_pk_bf16_f32 v101, v106, v107
	v_mfma_f32_32x32x16_bf16 v[16:31], v[212:215], v[96:99], v[16:31]
	v_exp_f32_e32 v108, v108
	v_exp_f32_e32 v109, v109
	v_exp_f32_e32 v110, v110
	v_exp_f32_e32 v111, v111
	v_cvt_pk_bf16_f32 v102, v108, v109
	v_cvt_pk_bf16_f32 v103, v110, v111
	v_mfma_f32_32x32x16_bf16 v[0:15], v[216:219], v[96:99], v[0:15]
	v_mfma_f32_16x16x32_bf16 v[152:155], v[156:159], v[96:99], v[152:155]
	v_exp_f32_e32 v64, v64
	v_exp_f32_e32 v65, v65
	v_exp_f32_e32 v66, v66
	v_exp_f32_e32 v67, v67
	v_cvt_pk_bf16_f32 v64, v64, v65
	v_cvt_pk_bf16_f32 v65, v66, v67
	v_mfma_f32_32x32x16_bf16 v[16:31], v[220:223], v[100:103], v[16:31]
	v_mfma_f32_32x32x16_bf16 v[0:15], v[224:227], v[100:103], v[0:15]
	v_exp_f32_e32 v68, v68
	v_exp_f32_e32 v69, v69
	v_exp_f32_e32 v70, v70
	v_exp_f32_e32 v71, v71
	v_cvt_pk_bf16_f32 v66, v68, v69
	v_cvt_pk_bf16_f32 v67, v70, v71
	v_mfma_f32_16x16x32_bf16 v[152:155], v[156:159], v[100:103], v[152:155]
	s_waitcnt lgkmcnt(2)
	v_mfma_f32_32x32x16_bf16 v[48:63], v[228:231], v[64:67], v[48:63]
	v_exp_f32_e32 v72, v72
	v_exp_f32_e32 v73, v73
	v_exp_f32_e32 v74, v74
	v_exp_f32_e32 v75, v75
	v_cvt_pk_bf16_f32 v68, v72, v73
	v_cvt_pk_bf16_f32 v69, v74, v75
	v_mfma_f32_32x32x16_bf16 v[32:47], v[180:183], v[64:67], v[32:47]
	v_mfma_f32_16x16x32_bf16 v[148:151], v[156:159], v[64:67], v[148:151]
	v_exp_f32_e32 v76, v76
	v_exp_f32_e32 v77, v77
	v_exp_f32_e32 v78, v78
	v_exp_f32_e32 v79, v79
	v_cvt_pk_bf16_f32 v70, v76, v77
	v_cvt_pk_bf16_f32 v71, v78, v79
	s_waitcnt lgkmcnt(0)
; #define MFMA32(a, b, c) __builtin_amdgcn_mfma_f32_32x32x16_bf16((a), (b), (c), 0, 0, 0)
; DI float fadd1(float a, float b) { float r; asm("v_add_f32 %0, %1, %2" : "=v"(r) : "v"(a), "v"(b)); return r; }
; template <int NKS>
; DI void attn_tile(const Params& p, int layer, int seq, int slot, int qt, char* smem, bool wr = true) {
;     ...
;       for (int kh = 0; kh < 2; ++kh) {
;       const u16* sK = (const u16*)(smem + (kt & 1) * 32768 + kh * 8192);
;       const u16* sV = (const u16*)(smem + (kt & 1) * 32768 + 16384 + kh * 8192);
;       auto kb_body = [&](int kb) {
;         bf16x8 kf[NKS];
; #pragma unroll
;         for (int ks = 0; ks < NKS; ++ks) kf[ks] = *(const bf16x8*)(sK + swz(32 * kb + r, 2 * (ks0 + ks) + h));
;         bf16x8 pk[2][2];
; #pragma unroll
;         for (int qb = 0; qb < 2; ++qb) {
;           f32x16 st;
; #pragma unroll
;           for (int i = 0; i < 16; ++i) st[i] = SUB ? ncb[qb] : 0.f;
; #pragma unroll
;           for (int ks = 0; ks < NKS; ++ks) st = MFMA32(kf[ks], qf[qb][ks], st);
;           if constexpr (SUB) {
;             float ls = 0.f;
; #pragma unroll
;             for (int i = 0; i < 16; ++i) { float e = __builtin_amdgcn_exp2f(st[i]); st[i] = e; ls = fadd1(ls, e); }
;             lsum[qb] += ls;
;             pk[qb][0] = pack8(st, 0); pk[qb][1] = pack8(st, 1);
;           } else {
; #pragma unroll
;             for (int i = 0; i < 16; ++i) st[i] = __builtin_amdgcn_exp2f(st[i]);
;             pk[qb][0] = pack8(st, 0); pk[qb][1] = pack8(st, 1);
;             ls4[qb] = __builtin_amdgcn_mfma_f32_16x16x32_bf16(selA, pk[qb][0], ls4[qb], 0, 0, 0);
;             ls4[qb] = __builtin_amdgcn_mfma_f32_16x16x32_bf16(selA, pk[qb][1], ls4[qb], 0, 0, 0);
;           }
;         }
; #pragma unroll
;         for (int eb = 0; eb < 2; ++eb)
; #pragma unroll
;           for (int s2 = 0; s2 < 2; ++s2) {
;             bf16x8 vf = *(const bf16x8*)(sV + swz(32 * eb + r, 4 * kb + 2 * s2 + h));
; #pragma unroll
;             for (int qb = 0; qb < 2; ++qb) O[qb][eb] = MFMA32(vf, pk[qb][s2], O[qb][eb]);
;           }
;       };
;       if constexpr (SUB) {
; #pragma unroll 1
;         for (int kb = 0; kb < 2; ++kb) kb_body(kb);
;       } else {
;         kb_body(0); kb_body(1);
;       }
	s_nop 0
	v_mfma_f32_32x32x16_bf16 v[48:63], v[184:187], v[68:71], v[48:63]
	v_exp_f32_e32 v80, v80
	v_exp_f32_e32 v81, v81
	v_exp_f32_e32 v82, v82
	v_exp_f32_e32 v83, v83
	v_cvt_pk_bf16_f32 v80, v80, v81
	v_cvt_pk_bf16_f32 v81, v82, v83
	v_mfma_f32_32x32x16_bf16 v[32:47], v[204:207], v[68:71], v[32:47]
	v_mfma_f32_16x16x32_bf16 v[148:151], v[156:159], v[68:71], v[148:151]
	v_exp_f32_e32 v84, v84
	v_exp_f32_e32 v85, v85
	v_exp_f32_e32 v86, v86
	v_exp_f32_e32 v87, v87
	v_cvt_pk_bf16_f32 v82, v84, v85
	v_cvt_pk_bf16_f32 v83, v86, v87
	v_exp_f32_e32 v88, v88
	v_exp_f32_e32 v89, v89
	v_exp_f32_e32 v90, v90
	v_exp_f32_e32 v91, v91
	v_cvt_pk_bf16_f32 v84, v88, v89
	v_cvt_pk_bf16_f32 v85, v90, v91
	v_mfma_f32_32x32x16_bf16 v[16:31], v[228:231], v[80:83], v[16:31]
	v_exp_f32_e32 v92, v92
	v_exp_f32_e32 v93, v93
	v_exp_f32_e32 v94, v94
	v_exp_f32_e32 v95, v95
	v_cvt_pk_bf16_f32 v86, v92, v93
	v_cvt_pk_bf16_f32 v87, v94, v95
	v_mfma_f32_32x32x16_bf16 v[0:15], v[180:183], v[80:83], v[0:15]
	v_mfma_f32_16x16x32_bf16 v[152:155], v[156:159], v[80:83], v[152:155]
	v_mfma_f32_32x32x16_bf16 v[16:31], v[184:187], v[84:87], v[16:31]
	v_mfma_f32_32x32x16_bf16 v[0:15], v[204:207], v[84:87], v[0:15]
	v_mfma_f32_16x16x32_bf16 v[152:155], v[156:159], v[84:87], v[152:155]
	ds_read_b128 v[180:183], v128 offset:8192
	ds_read_b128 v[184:187], v130 offset:8192
	ds_read_b128 v[204:207], v128 offset:12288
	ds_read_b128 v[208:211], v130 offset:12288
	ds_read_b128 v[212:215], v131 offset:24576
	ds_read_b128 v[216:219], v131 offset:28672
	ds_read_b128 v[220:223], v188 offset:24576
	ds_read_b128 v[224:227], v188 offset:28672
	ds_read_b128 v[228:231], v189 offset:24576
	s_waitcnt lgkmcnt(7)
	v_mfma_f32_32x32x16_bf16 v[112:127], v[180:183], v[132:135], 0
	v_mfma_f32_32x32x16_bf16 v[112:127], v[184:187], v[136:139], v[112:127]
	v_mfma_f32_32x32x16_bf16 v[96:111], v[180:183], v[140:143], 0
	v_mfma_f32_32x32x16_bf16 v[96:111], v[184:187], v[144:147], v[96:111]
	ds_read_b128 v[180:183], v189 offset:28672
	ds_read_b128 v[184:187], v190 offset:24576
	s_waitcnt lgkmcnt(7)
	v_mfma_f32_32x32x16_bf16 v[64:79], v[204:207], v[132:135], 0
	v_mfma_f32_32x32x16_bf16 v[64:79], v[208:211], v[136:139], v[64:79]
	s_nop 4
	v_exp_f32_e32 v112, v112
	v_exp_f32_e32 v113, v113
	v_exp_f32_e32 v114, v114
	v_exp_f32_e32 v115, v115
	v_cvt_pk_bf16_f32 v112, v112, v113
	v_cvt_pk_bf16_f32 v113, v114, v115
	v_mfma_f32_32x32x16_bf16 v[80:95], v[204:207], v[140:143], 0
	ds_read_b128 v[204:207], v190 offset:28672
	v_exp_f32_e32 v116, v116
	v_exp_f32_e32 v117, v117
	v_exp_f32_e32 v118, v118
	v_exp_f32_e32 v119, v119
	v_cvt_pk_bf16_f32 v114, v116, v117
	v_cvt_pk_bf16_f32 v115, v118, v119
	v_mfma_f32_32x32x16_bf16 v[80:95], v[208:211], v[144:147], v[80:95]
	v_exp_f32_e32 v120, v120
	v_exp_f32_e32 v121, v121
	v_exp_f32_e32 v122, v122
	v_exp_f32_e32 v123, v123
	v_cvt_pk_bf16_f32 v116, v120, v121
	v_cvt_pk_bf16_f32 v117, v122, v123
	s_waitcnt lgkmcnt(6)
	v_mfma_f32_32x32x16_bf16 v[48:63], v[212:215], v[112:115], v[48:63]
	v_exp_f32_e32 v124, v124
	v_exp_f32_e32 v125, v125
	v_exp_f32_e32 v126, v126
	v_exp_f32_e32 v127, v127
	v_cvt_pk_bf16_f32 v118, v124, v125
	v_cvt_pk_bf16_f32 v119, v126, v127
	v_mfma_f32_32x32x16_bf16 v[32:47], v[216:219], v[112:115], v[32:47]
	v_exp_f32_e32 v96, v96
	v_exp_f32_e32 v97, v97
	v_exp_f32_e32 v98, v98
	v_exp_f32_e32 v99, v99
	v_cvt_pk_bf16_f32 v96, v96, v97
	v_cvt_pk_bf16_f32 v97, v98, v99
	v_mfma_f32_16x16x32_bf16 v[148:151], v[156:159], v[112:115], v[148:151]
	s_waitcnt lgkmcnt(4)
	v_mfma_f32_32x32x16_bf16 v[48:63], v[220:223], v[116:119], v[48:63]
	v_exp_f32_e32 v100, v100
	v_exp_f32_e32 v101, v101
	v_exp_f32_e32 v102, v102
	v_exp_f32_e32 v103, v103
	v_cvt_pk_bf16_f32 v98, v100, v101
	v_cvt_pk_bf16_f32 v99, v102, v103
	v_mfma_f32_32x32x16_bf16 v[32:47], v[224:227], v[116:119], v[32:47]
	v_mfma_f32_16x16x32_bf16 v[148:151], v[156:159], v[116:119], v[148:151]
	v_exp_f32_e32 v104, v104
	v_exp_f32_e32 v105, v105
	v_exp_f32_e32 v106, v106
	v_exp_f32_e32 v107, v107
	v_cvt_pk_bf16_f32 v100, v104, v105
	v_cvt_pk_bf16_f32 v101, v106, v107
	v_mfma_f32_32x32x16_bf16 v[16:31], v[212:215], v[96:99], v[16:31]
	v_exp_f32_e32 v108, v108
	v_exp_f32_e32 v109, v109
	v_exp_f32_e32 v110, v110
	v_exp_f32_e32 v111, v111
	v_cvt_pk_bf16_f32 v102, v108, v109
	v_cvt_pk_bf16_f32 v103, v110, v111
	v_mfma_f32_32x32x16_bf16 v[0:15], v[216:219], v[96:99], v[0:15]
	v_mfma_f32_16x16x32_bf16 v[152:155], v[156:159], v[96:99], v[152:155]
	v_exp_f32_e32 v64, v64
	v_exp_f32_e32 v65, v65
	v_exp_f32_e32 v66, v66
	v_exp_f32_e32 v67, v67
	v_cvt_pk_bf16_f32 v64, v64, v65
	v_cvt_pk_bf16_f32 v65, v66, v67
	v_mfma_f32_32x32x16_bf16 v[16:31], v[220:223], v[100:103], v[16:31]
	v_mfma_f32_32x32x16_bf16 v[0:15], v[224:227], v[100:103], v[0:15]
	v_exp_f32_e32 v68, v68
	v_exp_f32_e32 v69, v69
	v_exp_f32_e32 v70, v70
	v_exp_f32_e32 v71, v71
	v_cvt_pk_bf16_f32 v66, v68, v69
	v_cvt_pk_bf16_f32 v67, v70, v71
	v_mfma_f32_16x16x32_bf16 v[152:155], v[156:159], v[100:103], v[152:155]
	s_waitcnt lgkmcnt(2)
	v_mfma_f32_32x32x16_bf16 v[48:63], v[228:231], v[64:67], v[48:63]
	v_exp_f32_e32 v72, v72
	v_exp_f32_e32 v73, v73
	v_exp_f32_e32 v74, v74
	v_exp_f32_e32 v75, v75
	v_cvt_pk_bf16_f32 v68, v72, v73
	v_cvt_pk_bf16_f32 v69, v74, v75
	v_mfma_f32_32x32x16_bf16 v[32:47], v[180:183], v[64:67], v[32:47]
	v_mfma_f32_16x16x32_bf16 v[148:151], v[156:159], v[64:67], v[148:151]
	v_exp_f32_e32 v76, v76
	v_exp_f32_e32 v77, v77
	v_exp_f32_e32 v78, v78
	v_exp_f32_e32 v79, v79
	v_cvt_pk_bf16_f32 v70, v76, v77
	v_cvt_pk_bf16_f32 v71, v78, v79
	s_waitcnt lgkmcnt(0)
	s_nop 0
	v_mfma_f32_32x32x16_bf16 v[48:63], v[184:187], v[68:71], v[48:63]
	v_exp_f32_e32 v80, v80
	v_exp_f32_e32 v81, v81
	v_exp_f32_e32 v82, v82
	v_exp_f32_e32 v83, v83
	v_cvt_pk_bf16_f32 v80, v80, v81
	v_cvt_pk_bf16_f32 v81, v82, v83
	v_mfma_f32_32x32x16_bf16 v[32:47], v[204:207], v[68:71], v[32:47]
	v_mfma_f32_16x16x32_bf16 v[148:151], v[156:159], v[68:71], v[148:151]
	v_exp_f32_e32 v84, v84
	v_exp_f32_e32 v85, v85
	v_exp_f32_e32 v86, v86
	v_exp_f32_e32 v87, v87
	v_cvt_pk_bf16_f32 v82, v84, v85
	v_cvt_pk_bf16_f32 v83, v86, v87
	v_exp_f32_e32 v88, v88
	v_exp_f32_e32 v89, v89
	v_exp_f32_e32 v90, v90
	v_exp_f32_e32 v91, v91
	v_cvt_pk_bf16_f32 v84, v88, v89
	v_cvt_pk_bf16_f32 v85, v90, v91
	v_mfma_f32_32x32x16_bf16 v[16:31], v[228:231], v[80:83], v[16:31]
	v_exp_f32_e32 v92, v92
	v_exp_f32_e32 v93, v93
	v_exp_f32_e32 v94, v94
	v_exp_f32_e32 v95, v95
	v_cvt_pk_bf16_f32 v86, v92, v93
	v_cvt_pk_bf16_f32 v87, v94, v95
	v_mfma_f32_32x32x16_bf16 v[0:15], v[180:183], v[80:83], v[0:15]
	v_mfma_f32_16x16x32_bf16 v[152:155], v[156:159], v[80:83], v[152:155]
	v_mfma_f32_32x32x16_bf16 v[16:31], v[184:187], v[84:87], v[16:31]
	v_mfma_f32_32x32x16_bf16 v[0:15], v[204:207], v[84:87], v[0:15]
	v_mfma_f32_16x16x32_bf16 v[152:155], v[156:159], v[84:87], v[152:155]
	s_cmp_eq_u32 s36, s31
	s_mov_b32 s37, s36
	s_cbranch_scc0 .LBB0_671

; template <int NKS>
; DI void attn_tile(const Params& p, int layer, int seq, int slot, int qt, char* smem, bool wr = true) {
;     ...
;   auto stage = [&](int kt) {
;     const int k0 = seq_start + kt * 128;
;     char* base = smem + (kt & 1) * 32768 + w * 1024;
; #pragma unroll
;     for (int i = 0; i < 4; ++i) {
;       __builtin_amdgcn_raw_ptr_buffer_load_lds(rK, (lds_ptr_t)(base + i * 4096), 16, voK, (k0 + 32 * i) * kstride * 2, 0, 0);
;       __builtin_amdgcn_raw_ptr_buffer_load_lds(rV, (lds_ptr_t)(base + 16384 + i * 4096), 16, voV,
;                                                (32 * (i & 1)) * (T_TOK * 2) + (k0 + 64 * (i >> 1)) * 2, 0, 0);
;     }
;   };
;     ...
;     for (int kt = 0; kt < nkt; ++kt) {
;       asm volatile("s_waitcnt vmcnt(0)" ::: "memory");
;       __syncthreads();
;       if (kt + 1 < nkt) stage(kt + 1);
; #pragma unroll 1
;       for (int kh = 0; kh < 2; ++kh) {
;       const u16* sK = (const u16*)(smem + (kt & 1) * 32768 + kh * 8192);
;       const u16* sV = (const u16*)(smem + (kt & 1) * 32768 + 16384 + kh * 8192);
;       auto kb_body = [&](int kb) {
;         bf16x8 kf[NKS];
; #pragma unroll
;         for (int ks = 0; ks < NKS; ++ks) kf[ks] = *(const bf16x8*)(sK + swz(32 * kb + r, 2 * (ks0 + ks) + h));
.LBB0_1414:
	s_waitcnt vmcnt(0)
	s_lshl_b32 s4, s37, 15
	s_and_b32 s4, s4, 0x8000
	v_add3_u32 v128, s4, v173, v179
	v_add3_u32 v130, s4, v174, v179
	v_add3_u32 v131, s4, v175, v179
	v_add3_u32 v188, s4, v176, v179
	v_add3_u32 v189, s4, v177, v179
	v_add3_u32 v190, s4, v178, v179
	s_add_i32 s36, s37, 1
	s_cmp_ge_u32 s36, s31
	s_barrier
	ds_read_b128 v[180:183], v128
	ds_read_b128 v[184:187], v130
	ds_read_b128 v[204:207], v128 offset:4096
	ds_read_b128 v[208:211], v130 offset:4096
	ds_read_b128 v[212:215], v131 offset:16384
	ds_read_b128 v[216:219], v131 offset:20480
	ds_read_b128 v[220:223], v188 offset:16384
	ds_read_b128 v[224:227], v188 offset:20480
	ds_read_b128 v[228:231], v189 offset:16384
	s_cbranch_scc1 .LBB0_1416
	s_lshl_b32 s4, s36, 15
	s_and_b32 s4, s4, 0x8000
	s_lshl_b32 s14, s36, 8
	s_add_i32 s4, s34, s4
	s_add_i32 s38, s14, s35
	s_add_i32 s5, s4, 0x4000
	s_lshl_b32 s39, s38, 8
	s_mov_b32 m0, s4
	s_mov_b32 s14, s10
	buffer_load_dwordx4 v171, s[8:11], s39 offen lds
	s_mov_b32 s15, s11
	s_mov_b32 m0, s5
	s_or_b32 s5, s39, 0x4000
	buffer_load_dwordx4 v172, s[12:15], s38 offen lds
	s_add_i32 m0, s4, 0x1000
	s_nop 0
	buffer_load_dwordx4 v171, s[8:11], s5 offen lds
	s_add_i32 m0, s4, 0x5000
	s_add_i32 s5, s38, 0x300000
	buffer_load_dwordx4 v172, s[12:15], s5 offen lds
	s_or_b32 s5, s38, 0x80
	s_add_i32 m0, s4, 0x2000
	s_lshl_b32 s40, s5, 8
	buffer_load_dwordx4 v171, s[8:11], s40 offen lds
	s_add_i32 m0, s4, 0x6000
	s_add_i32 s38, s38, 0x300080
	buffer_load_dwordx4 v172, s[12:15], s5 offen lds
	s_add_i32 m0, s4, 0x3000
	s_or_b32 s5, s39, 0xc000
	buffer_load_dwordx4 v171, s[8:11], s5 offen lds
	s_add_i32 m0, s4, 0x7000
	s_nop 0
	buffer_load_dwordx4 v172, s[12:15], s38 offen lds
